# G4 epilogue v2: row scales read up front, next tile's first fragments read in the background of row groups 4-7 (peeled phase 1 only issues its 2 DMA loads)
# baseline (speedup 1.0000x reference)
; #define PG8_STAGE(bufoff, gbase, voff) do { _Pragma("unroll") for (int _i = 0; _i < 2; ++_i) \
;         __builtin_amdgcn_global_load_lds((const unsigned*)((const char*)(gbase) + (voff)[_i]), (PG8_LAS unsigned*)(lds + (bufoff) + ldsw + _i * 8192), 16, 0, 0); } while (0)
; #define PG8_LDA(dst, b, h) do { _Pragma("unroll") for (int m = 0; m < 4; ++m) _Pragma("unroll") for (int k = 0; k < 2; ++k) dst[m][k] = *(const PG8_LAS bf16x8*)(lds + PG8_SA(b, h) + aoff + m * 2048 + k * 1024); } while (0)
; #define PG8_LDB(dst, b, h) do { _Pragma("unroll") for (int n = 0; n < 2; ++n) _Pragma("unroll") for (int k = 0; k < 2; ++k) dst[n][k] = *(const PG8_LAS bf16x8*)(lds + PG8_SB(b, h) + boff + n * 2048 + k * 1024); } while (0)
; #define PG8_WAIT_V(n) asm volatile("s_waitcnt vmcnt(" #n ")" ::: "memory")
; #define PG8_BAR __builtin_amdgcn_s_barrier()
; #define PG8_SCHED __builtin_amdgcn_sched_barrier(0)
; template <class Epi, class Sched>
; __device__ __forceinline__ void gemm_phase(PG8_LAS unsigned char* lds, const Gemm g, const Sched& S, const Epi& E) {
;     ...
;     PG8_STAGE(PG8_SB(0, 0), cB, voffB); PG8_STAGE(PG8_SB(0, 1), cB + hstepB, voffB); PG8_STAGE(PG8_SA(0, 0), cA, voffA); PG8_STAGE(PG8_SA(0, 1), cA + hstepA, voffA);
;     if (wr == 1) PG8_BAR;
;     PG8_WAIT_V(2); PG8_BAR;
;     PG8_STAGE(PG8_SB(1, 0), cB + kstep, voffB); PG8_STAGE(PG8_SA(1, 0), cA + kstep, voffA); PG8_STAGE(PG8_SB(1, 1), cB + hstepB + kstep, voffB);
;     PG8_WAIT_V(6); PG8_BAR;
;     ...
;             PG8_LDB(B0, 0, 0); PG8_LDB(B1, 0, 1); PG8_SCHED; PG8_LDA(At, 0, 0); PG8_STAGE(PG8_SA(1, 1), a1 + hstepA, voffA);
.LBB0_572:
	v_lshrrev_b32_e32 v18, 1, v2
	v_and_b32_e32 v18, 24, v18
	v_and_b32_e32 v13, 15, v2
	v_lshlrev_b32_e32 v19, 1, v18
	s_lshl_b32 s0, s0, 5
	v_lshl_or_b32 v1, s11, 6, v13
	v_lshl_or_b32 v19, v13, 6, v19
	v_lshlrev_b32_e32 v13, 2, v13
	s_and_b32 s12, s0, 0x60
	s_waitcnt vmcnt(0)
	v_and_b32_e32 v20, 32, v13
	s_lshl_b32 s1, s11, 13
	s_lshl_b32 s0, s12, 7
	v_readlane_b32 s22, v253, 52
	v_bitop3_b32 v150, v19, s0, v20 bitop3:0xde
	s_add_u32 s0, s24, 0x40080
	v_mov_b32_e32 v135, v0
	v_readlane_b32 s23, v253, 53
	v_bitop3_b32 v21, v19, s1, v20 bitop3:0xde
	s_addc_u32 s1, s25, 0
	s_add_i32 m0, s31, 0x18000
	v_lshl_add_u64 v[4:5], v[4:5], 0, s[78:79]
	v_lshl_add_u64 v[14:15], s[22:23], 0, v[134:135]
	v_mov_b32_e32 v139, v0
	s_waitcnt vmcnt(2)
	s_barrier
	global_load_lds_dwordx4 v[4:5], off
	v_lshl_add_u64 v[4:5], v[6:7], 0, s[78:79]
	s_add_i32 m0, s31, 0x1a000
	s_add_i32 s71, s31, 0x8000
	v_lshl_add_u64 v[16:17], s[22:23], 0, v[138:139]
	global_load_lds_dwordx4 v[4:5], off
	v_lshl_add_u64 v[4:5], v[14:15], 0, s[78:79]
	s_mov_b32 m0, s71
	s_add_i32 s74, s31, 0xa000
	global_load_lds_dwordx4 v[4:5], off
	v_lshl_add_u64 v[4:5], v[16:17], 0, s[78:79]
	s_mov_b32 m0, s74
	v_readlane_b32 s14, v254, 16
	global_load_lds_dwordx4 v[4:5], off
	s_add_i32 m0, s31, 0x1c000
	v_lshl_add_u64 v[4:5], s[0:1], 0, v[136:137]
	global_load_lds_dwordx4 v[4:5], off
	v_lshl_add_u64 v[4:5], s[0:1], 0, v[140:141]
	s_add_i32 m0, s31, 0x1e000
	s_movk_i32 s0, 0xffc0
	global_load_lds_dwordx4 v[4:5], off
	v_mov_b32_e32 v4, s10
	v_bfi_b32 v4, s0, v4, v2
	v_lshlrev_b32_e32 v2, 14, v3
	v_and_b32_e32 v2, 0xffff8000, v2
	v_lshl_add_u32 v2, v8, 11, v2
	v_and_b32_e32 v3, 1, v3
	v_lshl_or_b32 v2, v3, 6, v2
	s_cmpk_lt_u32 s10, 0x100
	v_lshl_add_u32 v144, v9, 1, v2
	v_lshlrev_b32_e32 v2, 14, v10
	s_cselect_b64 s[8:9], -1, 0
	s_lshl_b32 s10, s11, 8
	s_add_i32 s11, 0, 0x22800
	v_and_b32_e32 v2, 0xffff8000, v2
	s_waitcnt vmcnt(6)
	s_add_i32 s10, s11, s10
	v_lshl_add_u32 v2, v11, 11, v2
	v_and_b32_e32 v3, 1, v10
	s_movk_i32 s0, 0x100
	v_ashrrev_i32_e32 v5, 31, v4
	v_readlane_b32 s15, v254, 17
	v_add_u32_e32 v151, s10, v13
	v_lshl_add_u32 v152, v4, 2, s11
	v_lshl_or_b32 v2, v3, 6, v2
	v_readlane_b32 s10, v253, 46
	v_cmp_gt_i32_e64 s[0:1], s0, v4
	v_lshl_add_u64 v[142:143], v[4:5], 4, s[14:15]
	v_or_b32_e32 v153, s12, v18
	v_mov_b32_e32 v145, v0
	v_lshl_add_u32 v146, v12, 1, v2
	v_mov_b32_e32 v147, v0
	s_mov_b32 s82, 0
	v_add_u32_e32 v154, 0, v21
	s_mov_b32 s12, s10
	s_mov_b32 s13, s67
	s_barrier
	v_add_u32_e32 v234, 0x10000, v150
	v_add_u32_e32 v235, 0x14000, v150
	ds_read_b128 v[98:101], v234
	ds_read_b128 v[156:159], v234 offset:1024
	ds_read_b128 v[160:163], v234 offset:2048
	ds_read_b128 v[164:167], v234 offset:3072
	ds_read_b128 v[168:171], v235
	ds_read_b128 v[172:175], v235 offset:1024
	ds_read_b128 v[176:179], v235 offset:2048
	ds_read_b128 v[180:183], v235 offset:3072
	ds_read_b128 v[184:187], v154
	ds_read_b128 v[188:191], v154 offset:1024
	ds_read_b128 v[192:195], v154 offset:2048
	ds_read_b128 v[196:199], v154 offset:3072
	ds_read_b128 v[200:203], v154 offset:4096
	ds_read_b128 v[204:207], v154 offset:5120
	ds_read_b128 v[208:211], v154 offset:6144
	ds_read_b128 v[214:217], v154 offset:7168
	v_readlane_b32 s11, v253, 47
	s_branch .LBB0_575

; #define PG8_STAGE(bufoff, gbase, voff) do { _Pragma("unroll") for (int _i = 0; _i < 2; ++_i) \
;         __builtin_amdgcn_global_load_lds((const unsigned*)((const char*)(gbase) + (voff)[_i]), (PG8_LAS unsigned*)(lds + (bufoff) + ldsw + _i * 8192), 16, 0, 0); } while (0)
; #define PG8_LDA(dst, b, h) do { _Pragma("unroll") for (int m = 0; m < 4; ++m) _Pragma("unroll") for (int k = 0; k < 2; ++k) dst[m][k] = *(const PG8_LAS bf16x8*)(lds + PG8_SA(b, h) + aoff + m * 2048 + k * 1024); } while (0)
; #define PG8_LDB(dst, b, h) do { _Pragma("unroll") for (int n = 0; n < 2; ++n) _Pragma("unroll") for (int k = 0; k < 2; ++k) dst[n][k] = *(const PG8_LAS bf16x8*)(lds + PG8_SB(b, h) + boff + n * 2048 + k * 1024); } while (0)
; #define PG8_MMA(ai, bj, At, Bt) do { __builtin_amdgcn_s_setprio(1); _Pragma("unroll") for (int m = 0; m < 4; ++m) _Pragma("unroll") for (int n = 0; n < 2; ++n) _Pragma("unroll") for (int k = 0; k < 2; ++k) \
;         acc[ai][bj][m][n] = __builtin_amdgcn_mfma_f32_16x16x32_bf16(Bt[n][k], At[m][k], acc[ai][bj][m][n], 0, 0, 0); __builtin_amdgcn_s_setprio(0); } while (0)
; #define PG8_WAIT_V(n) asm volatile("s_waitcnt vmcnt(" #n ")" ::: "memory")
; template <class Epi, class Sched>
; __device__ __forceinline__ void gemm_phase(PG8_LAS unsigned char* lds, const Gemm g, const Sched& S, const Epi& E) {
;     ...
;         const char* nA = has_next ? (const char*)g.A + (size_t)nxt.pm * tstepA : cA; const char* nB = has_next ? (const char*)g.Bt + (size_t)nxt.pn * tstepB : cB;
;         for (int t = 0; t < nt; t += 2) {
;             const bool last = (t == nt - 2);
;             const char* a1 = cA + (size_t)(t + 1) * kstep;
;             const char* a2 = last ? nA : cA + (size_t)(t + 2) * kstep; const char* b2 = last ? nB : cB + (size_t)(t + 2) * kstep;
;             const char* a3 = a2 + kstep; const char* b3 = b2 + kstep;
;             PG8_LDB(B0, 0, 0); PG8_LDB(B1, 0, 1); PG8_SCHED; PG8_LDA(At, 0, 0); PG8_STAGE(PG8_SA(1, 1), a1 + hstepA, voffA);
;             PG8_WAIT_V(8); PG8_WAIT_L(0); PG8_BAR; PG8_MMA(0, 0, At, B0); PG8_MMA(0, 1, At, B1); PG8_BAR; PG8_SCHED;
;             PG8_LDA(At, 0, 1); PG8_STAGE(PG8_SB(0, 0), b2, voffB); PG8_STAGE(PG8_SB(0, 1), b2 + hstepB, voffB); PG8_STAGE(PG8_SA(0, 0), a2, voffA);
;             PG8_WAIT_V(8); PG8_WAIT_L(0); PG8_BAR; PG8_MMA(1, 0, At, B0); PG8_MMA(1, 1, At, B1); PG8_BAR; PG8_SCHED;
.LBB0_580:
	s_ashr_i32 s11, s10, 31
	s_lshl_b64 s[16:17], s[10:11], 19
	s_add_u32 s16, s36, s16
	s_addc_u32 s17, s37, s17
	s_and_b64 s[18:19], s[20:21], exec
	s_cselect_b32 s33, s17, s23
	s_cselect_b32 s46, s16, s22
	s_ashr_i32 s15, s14, 31
	s_lshl_b64 s[18:19], s[14:15], 19
	s_add_u32 s18, s29, s18
	s_addc_u32 s19, s30, s19
	s_and_b64 s[26:27], s[20:21], exec
	s_cselect_b32 s15, s19, s25
	s_cselect_b32 s47, s18, s24
	s_add_u32 s22, s22, 0x40080
	s_addc_u32 s23, s23, 0
	s_add_u32 s48, s24, 0x100
	v_mov_b32_e32 v2, 0
	s_addc_u32 s49, s25, 0
	s_mov_b32 s57, -2
	s_add_u32 s24, s22, 0xfffc0080
	s_addc_u32 s25, s23, -1
	s_add_i32 s58, 0, 0x10000
	s_cmp_eq_u32 s57, 12
	s_cselect_b32 s27, s33, s25
	s_cselect_b32 s26, s46, s24
	s_cselect_b32 s25, s15, s49
	s_cselect_b32 s24, s47, s48
	s_add_i32 s64, 0, 0x14000
	v_lshl_add_u64 v[148:149], s[22:23], 0, v[144:145]
	s_add_i32 m0, s31, 0xc000
	global_load_lds_dwordx4 v[148:149], off
	v_lshl_add_u64 v[148:149], s[22:23], 0, v[146:147]
	s_add_i32 m0, s31, 0xe000
	s_nop 0
	global_load_lds_dwordx4 v[148:149], off
	s_waitcnt vmcnt(16)
	s_waitcnt lgkmcnt(0)
	s_barrier
	s_setprio 1
	s_waitcnt lgkmcnt(0)
	v_mfma_f32_16x16x32_bf16 v[130:133], v[98:101], v[184:187], 0
	v_mfma_f32_16x16x32_bf16 v[126:129], v[160:163], v[184:187], 0
	v_mfma_f32_16x16x32_bf16 v[114:117], v[98:101], v[192:195], 0
	v_mfma_f32_16x16x32_bf16 v[110:113], v[160:163], v[192:195], 0
	v_mfma_f32_16x16x32_bf16 v[94:97], v[98:101], v[200:203], 0
	v_mfma_f32_16x16x32_bf16 v[90:93], v[160:163], v[200:203], 0
	v_mfma_f32_16x16x32_bf16 v[78:81], v[98:101], v[208:211], 0
	v_mfma_f32_16x16x32_bf16 v[74:77], v[160:163], v[208:211], 0
	v_mfma_f32_16x16x32_bf16 v[130:133], v[156:159], v[188:191], v[130:133]
	v_mfma_f32_16x16x32_bf16 v[126:129], v[164:167], v[188:191], v[126:129]
	v_mfma_f32_16x16x32_bf16 v[114:117], v[156:159], v[196:199], v[114:117]
	v_mfma_f32_16x16x32_bf16 v[110:113], v[164:167], v[196:199], v[110:113]
	v_mfma_f32_16x16x32_bf16 v[94:97], v[156:159], v[204:207], v[94:97]
	v_mfma_f32_16x16x32_bf16 v[90:93], v[164:167], v[204:207], v[90:93]
	v_mfma_f32_16x16x32_bf16 v[78:81], v[156:159], v[214:217], v[78:81]
	v_mfma_f32_16x16x32_bf16 v[74:77], v[164:167], v[214:217], v[74:77]
	s_setprio 0
	s_setprio 1
	v_mfma_f32_16x16x32_bf16 v[122:125], v[168:171], v[184:187], 0
	v_mfma_f32_16x16x32_bf16 v[118:121], v[176:179], v[184:187], 0
	v_mfma_f32_16x16x32_bf16 v[106:109], v[168:171], v[192:195], 0
	v_mfma_f32_16x16x32_bf16 v[102:105], v[176:179], v[192:195], 0
	v_mfma_f32_16x16x32_bf16 v[86:89], v[168:171], v[200:203], 0
	v_mfma_f32_16x16x32_bf16 v[82:85], v[176:179], v[200:203], 0
	v_mfma_f32_16x16x32_bf16 v[70:73], v[168:171], v[208:211], 0
	v_mfma_f32_16x16x32_bf16 v[66:69], v[176:179], v[208:211], 0
	v_mfma_f32_16x16x32_bf16 v[122:125], v[172:175], v[188:191], v[122:125]
	v_mfma_f32_16x16x32_bf16 v[118:121], v[180:183], v[188:191], v[118:121]
	v_mfma_f32_16x16x32_bf16 v[106:109], v[172:175], v[196:199], v[106:109]
	v_mfma_f32_16x16x32_bf16 v[102:105], v[180:183], v[196:199], v[102:105]
	v_mfma_f32_16x16x32_bf16 v[86:89], v[172:175], v[204:207], v[86:89]
	v_mfma_f32_16x16x32_bf16 v[82:85], v[180:183], v[204:207], v[82:85]
	v_mfma_f32_16x16x32_bf16 v[70:73], v[172:175], v[214:217], v[70:73]
	v_mfma_f32_16x16x32_bf16 v[66:69], v[180:183], v[214:217], v[66:69]
	s_setprio 0
	s_barrier
	s_add_i32 s58, s58, s28
	v_lshl_add_u64 v[148:149], s[24:25], 0, v[136:137]
	s_mov_b32 m0, s58
	ds_read_b128 v[184:187], v154 offset:16384
	ds_read_b128 v[188:191], v154 offset:17408
	ds_read_b128 v[192:195], v154 offset:18432
	ds_read_b128 v[196:199], v154 offset:19456
	ds_read_b128 v[200:203], v154 offset:20480
	ds_read_b128 v[204:207], v154 offset:21504
	ds_read_b128 v[208:211], v154 offset:22528
	ds_read_b128 v[214:217], v154 offset:23552
	global_load_lds_dwordx4 v[148:149], off
	s_add_i32 m0, s58, 0x2000
	s_add_u32 s58, s24, 0x40000
	v_lshl_add_u64 v[212:213], s[24:25], 0, v[140:141]
	s_addc_u32 s59, s25, 0
	s_add_i32 s64, s64, s28
	global_load_lds_dwordx4 v[212:213], off
	v_lshl_add_u64 v[218:219], s[58:59], 0, v[136:137]
	s_mov_b32 m0, s64
	v_lshl_add_u64 v[220:221], s[26:27], 0, v[138:139]
	global_load_lds_dwordx4 v[218:219], off
	v_lshl_add_u64 v[218:219], s[58:59], 0, v[140:141]
	s_add_i32 m0, s64, 0x2000
	s_nop 0
	global_load_lds_dwordx4 v[218:219], off
	v_lshl_add_u64 v[218:219], s[26:27], 0, v[134:135]
	s_mov_b32 m0, s31
	s_nop 0
	global_load_lds_dwordx4 v[218:219], off
	s_mov_b32 m0, s60
	s_nop 0
	global_load_lds_dwordx4 v[220:221], off
	s_waitcnt vmcnt(8)
	s_waitcnt lgkmcnt(0)
	s_barrier
	s_setprio 1
	s_waitcnt lgkmcnt(0)
	v_mfma_f32_16x16x32_bf16 v[62:65], v[98:101], v[184:187], 0
	v_mfma_f32_16x16x32_bf16 v[58:61], v[160:163], v[184:187], 0
	v_mfma_f32_16x16x32_bf16 v[46:49], v[98:101], v[192:195], 0
	v_mfma_f32_16x16x32_bf16 v[42:45], v[160:163], v[192:195], 0
	v_mfma_f32_16x16x32_bf16 v[30:33], v[98:101], v[200:203], 0
	v_mfma_f32_16x16x32_bf16 v[26:29], v[160:163], v[200:203], 0
	v_mfma_f32_16x16x32_bf16 v[14:17], v[98:101], v[208:211], 0
	v_mfma_f32_16x16x32_bf16 v[10:13], v[160:163], v[208:211], 0
	v_mfma_f32_16x16x32_bf16 v[62:65], v[156:159], v[188:191], v[62:65]
	v_mfma_f32_16x16x32_bf16 v[58:61], v[164:167], v[188:191], v[58:61]
	v_mfma_f32_16x16x32_bf16 v[46:49], v[156:159], v[196:199], v[46:49]
	v_mfma_f32_16x16x32_bf16 v[42:45], v[164:167], v[196:199], v[42:45]
	v_mfma_f32_16x16x32_bf16 v[30:33], v[156:159], v[204:207], v[30:33]
	v_mfma_f32_16x16x32_bf16 v[26:29], v[164:167], v[204:207], v[26:29]
	v_mfma_f32_16x16x32_bf16 v[14:17], v[156:159], v[214:217], v[14:17]
	v_mfma_f32_16x16x32_bf16 v[10:13], v[164:167], v[214:217], v[10:13]
	s_setprio 0
	s_setprio 1
	v_mfma_f32_16x16x32_bf16 v[54:57], v[168:171], v[184:187], 0
	v_mfma_f32_16x16x32_bf16 v[50:53], v[176:179], v[184:187], 0
	v_mfma_f32_16x16x32_bf16 v[38:41], v[168:171], v[192:195], 0
	v_mfma_f32_16x16x32_bf16 v[34:37], v[176:179], v[192:195], 0
	v_mfma_f32_16x16x32_bf16 v[22:25], v[168:171], v[200:203], 0
	v_mfma_f32_16x16x32_bf16 v[18:21], v[176:179], v[200:203], 0
	v_mfma_f32_16x16x32_bf16 v[6:9], v[168:171], v[208:211], 0
	v_mfma_f32_16x16x32_bf16 v[2:5], v[176:179], v[208:211], 0
	v_mfma_f32_16x16x32_bf16 v[54:57], v[172:175], v[188:191], v[54:57]
	v_mfma_f32_16x16x32_bf16 v[50:53], v[180:183], v[188:191], v[50:53]
	v_mfma_f32_16x16x32_bf16 v[38:41], v[172:175], v[196:199], v[38:41]
	v_mfma_f32_16x16x32_bf16 v[34:37], v[180:183], v[196:199], v[34:37]
	v_mfma_f32_16x16x32_bf16 v[22:25], v[172:175], v[204:207], v[22:25]
	v_mfma_f32_16x16x32_bf16 v[18:21], v[180:183], v[204:207], v[18:21]
	v_mfma_f32_16x16x32_bf16 v[6:9], v[172:175], v[214:217], v[6:9]
	v_mfma_f32_16x16x32_bf16 v[2:5], v[180:183], v[214:217], v[2:5]
	s_setprio 0
	s_barrier
	s_branch .Lpeel_mid_581

; __device__ __forceinline__ unsigned cvt_pk_bf16(float lo, float hi) { unsigned r; asm volatile("v_cvt_pk_bf16_f32 %0, %1, %2" : "=v"(r) : "v"(lo), "v"(hi)); return r; }
; #define LAS __attribute__((address_space(3)))
; __device__ __forceinline__ float sigmoid_f(float x) { return __builtin_amdgcn_rcpf(1.0f + __builtin_amdgcn_exp2f(-1.4426950408889634f * x)); }
;     __device__ __forceinline__ void operator()(const f32x4 (&acc)[2][2][4][2], const pg8::Unit& u, int wr, int wc, int fr, int fq, LAS unsigned char* lds, int wid, int lane, const pg8::Unit& nxt, bool has_next, int ui) const {
;         const int row0 = u.pm * 256 + wr * 64 + fr, col = u.pn * 128 + wc * 32 + fq * 8, tid = wid * 64 + lane;
;         const LAS float* R = (const LAS float*)(lds + RS_OFF) + (ui & 1) * 256;
;         const bool pre = has_next && tid < 256; f32x4 qn = (f32x4){1.f, 1.f, 1.f, 1.f};
;         if (pre) qn = *(const f32x4*)(rss + ((size_t)nxt.pm * 256 + tid) * 4);
; #pragma unroll
;         for (int ai = 0; ai < 2; ++ai) {
; #pragma unroll
;             for (int m = 0; m < 4; ++m) {
;                 const int row = row0 + ai * 128 + m * 16; const float r_ = R[wr * 64 + fr + ai * 128 + m * 16];
;                 const f32x4 g0 = acc[ai][0][m][0] * r_, g1 = acc[ai][0][m][1] * r_, u0 = acc[ai][1][m][0] * r_, u1 = acc[ai][1][m][1] * r_;
;                 v4u w;
;                 w.x = cvt_pk_bf16(g0[0] * sigmoid_f(g0[0]) * u0[0], g0[1] * sigmoid_f(g0[1]) * u0[1]); w.y = cvt_pk_bf16(g0[2] * sigmoid_f(g0[2]) * u0[2], g0[3] * sigmoid_f(g0[3]) * u0[3]);
;                 w.z = cvt_pk_bf16(g1[0] * sigmoid_f(g1[0]) * u1[0], g1[1] * sigmoid_f(g1[1]) * u1[1]); w.w = cvt_pk_bf16(g1[2] * sigmoid_f(g1[2]) * u1[2], g1[3] * sigmoid_f(g1[3]) * u1[3]);
;                 *(v4u*)(ACT + (size_t)row * FF + col) = w;
.LBB0_586:
	s_or_b64 exec, exec, s[22:23]
	s_lshl_b32 s11, s82, 8
	s_and_b32 s11, s11, 0x100
	v_lshl_add_u32 v155, s11, 2, v151
	ds_read_b32 v227, v155
	ds_read_b32 v232, v155 offset:64
	ds_read_b32 v237, v155 offset:128
	ds_read_b32 v238, v155 offset:192
	ds_read_b32 v239, v155 offset:512
	ds_read_b32 v240, v155 offset:576
	ds_read_b32 v241, v155 offset:640
	ds_read_b32 v242, v155 offset:704
	v_lshl_or_b32 v148, s12, 7, v153
	v_lshl_add_u32 v236, s13, 8, v1
	v_ashrrev_i32_e32 v149, 31, v148
	v_lshlrev_b64 v[224:225], 1, v[148:149]
	v_lshl_add_u64 v[224:225], v[224:225], 0, s[40:41]
	s_waitcnt lgkmcnt(0)
	v_mul_f32_e32 v230, 0xbfb8aa3b, v227
	v_mul_f32_e32 v231, v227, v227
	v_rcp_f32_e32 v231, v231
	v_mul_f32_e32 v122, v130, v122
	v_mul_f32_e32 v123, v131, v123
	v_mul_f32_e32 v124, v132, v124
	v_mul_f32_e32 v125, v133, v125
	v_mul_f32_e32 v118, v126, v118
	v_mul_f32_e32 v119, v127, v119
	v_mul_f32_e32 v120, v128, v120
	v_mul_f32_e32 v121, v129, v121
	v_mul_f32_e32 v130, v230, v130
	v_mul_f32_e32 v131, v230, v131
	v_mul_f32_e32 v132, v230, v132
	v_mul_f32_e32 v133, v230, v133
	v_mul_f32_e32 v126, v230, v126
	v_mul_f32_e32 v127, v230, v127
	v_mul_f32_e32 v128, v230, v128
	v_mul_f32_e32 v129, v230, v129
	v_exp_f32_e32 v130, v130
	v_exp_f32_e32 v131, v131
	v_exp_f32_e32 v132, v132
	v_exp_f32_e32 v133, v133
	v_exp_f32_e32 v126, v126
	v_exp_f32_e32 v127, v127
	v_exp_f32_e32 v128, v128
	v_exp_f32_e32 v129, v129
	v_fma_f32 v130, v130, v231, v231
	v_fma_f32 v131, v131, v231, v231
	v_fma_f32 v132, v132, v231, v231
	v_fma_f32 v133, v133, v231, v231
	v_fma_f32 v126, v126, v231, v231
	v_fma_f32 v127, v127, v231, v231
	v_fma_f32 v128, v128, v231, v231
	v_fma_f32 v129, v129, v231, v231
	v_rcp_f32_e32 v130, v130
	v_rcp_f32_e32 v131, v131
	v_rcp_f32_e32 v132, v132
	v_rcp_f32_e32 v133, v133
	v_rcp_f32_e32 v126, v126
	v_rcp_f32_e32 v127, v127
	v_rcp_f32_e32 v128, v128
	v_rcp_f32_e32 v129, v129
	v_mul_f32_e32 v122, v122, v130
	v_mul_f32_e32 v123, v123, v131
	v_mul_f32_e32 v124, v124, v132
	v_mul_f32_e32 v125, v125, v133
	v_mul_f32_e32 v118, v118, v126
	v_mul_f32_e32 v119, v119, v127
	v_mul_f32_e32 v120, v120, v128
	v_mul_f32_e32 v121, v121, v129
	v_cvt_pk_bf16_f32 v122, v122, v123
	v_cvt_pk_bf16_f32 v123, v124, v125
	v_cvt_pk_bf16_f32 v124, v118, v119
	v_cvt_pk_bf16_f32 v125, v120, v121
	v_mov_b32_e32 v226, v236
	v_mad_i64_i32 v[228:229], s[12:13], v226, s55, v[224:225]
	global_store_dwordx4 v[228:229], v[122:125], off
	v_mul_f32_e32 v230, 0xbfb8aa3b, v232
	v_mul_f32_e32 v231, v232, v232
	v_rcp_f32_e32 v231, v231
	v_mul_f32_e32 v106, v114, v106
	v_mul_f32_e32 v107, v115, v107
	v_mul_f32_e32 v108, v116, v108
	v_mul_f32_e32 v109, v117, v109
	v_mul_f32_e32 v102, v110, v102
	v_mul_f32_e32 v103, v111, v103
	v_mul_f32_e32 v104, v112, v104
	v_mul_f32_e32 v105, v113, v105
	v_mul_f32_e32 v114, v230, v114
	v_mul_f32_e32 v115, v230, v115
	v_mul_f32_e32 v116, v230, v116
	v_mul_f32_e32 v117, v230, v117
	v_mul_f32_e32 v110, v230, v110
	v_mul_f32_e32 v111, v230, v111
	v_mul_f32_e32 v112, v230, v112
	v_mul_f32_e32 v113, v230, v113
	v_exp_f32_e32 v114, v114
	v_exp_f32_e32 v115, v115
	v_exp_f32_e32 v116, v116
	v_exp_f32_e32 v117, v117
	v_exp_f32_e32 v110, v110
	v_exp_f32_e32 v111, v111
	v_exp_f32_e32 v112, v112
	v_exp_f32_e32 v113, v113
	v_fma_f32 v114, v114, v231, v231
	v_fma_f32 v115, v115, v231, v231
	v_fma_f32 v116, v116, v231, v231
	v_fma_f32 v117, v117, v231, v231
	v_fma_f32 v110, v110, v231, v231
	v_fma_f32 v111, v111, v231, v231
	v_fma_f32 v112, v112, v231, v231
	v_fma_f32 v113, v113, v231, v231
	v_rcp_f32_e32 v114, v114
	v_rcp_f32_e32 v115, v115
	v_rcp_f32_e32 v116, v116
	v_rcp_f32_e32 v117, v117
	v_rcp_f32_e32 v110, v110
	v_rcp_f32_e32 v111, v111
	v_rcp_f32_e32 v112, v112
	v_rcp_f32_e32 v113, v113
	v_mul_f32_e32 v106, v106, v114
	v_mul_f32_e32 v107, v107, v115
	v_mul_f32_e32 v108, v108, v116
	v_mul_f32_e32 v109, v109, v117
	v_mul_f32_e32 v102, v102, v110
	v_mul_f32_e32 v103, v103, v111
	v_mul_f32_e32 v104, v104, v112
	v_mul_f32_e32 v105, v105, v113
	v_cvt_pk_bf16_f32 v106, v106, v107
	v_cvt_pk_bf16_f32 v107, v108, v109
	v_cvt_pk_bf16_f32 v108, v102, v103
	v_cvt_pk_bf16_f32 v109, v104, v105
	v_or_b32_e32 v226, 16, v236
	v_mad_i64_i32 v[228:229], s[12:13], v226, s55, v[224:225]
	global_store_dwordx4 v[228:229], v[106:109], off
	v_mul_f32_e32 v230, 0xbfb8aa3b, v237
	v_mul_f32_e32 v231, v237, v237
	v_rcp_f32_e32 v231, v231
	v_mul_f32_e32 v86, v94, v86
	v_mul_f32_e32 v87, v95, v87
	v_mul_f32_e32 v88, v96, v88
	v_mul_f32_e32 v89, v97, v89
	v_mul_f32_e32 v82, v90, v82
	v_mul_f32_e32 v83, v91, v83
	v_mul_f32_e32 v84, v92, v84
	v_mul_f32_e32 v85, v93, v85
	v_mul_f32_e32 v94, v230, v94
	v_mul_f32_e32 v95, v230, v95
	v_mul_f32_e32 v96, v230, v96
	v_mul_f32_e32 v97, v230, v97
	v_mul_f32_e32 v90, v230, v90
	v_mul_f32_e32 v91, v230, v91
	v_mul_f32_e32 v92, v230, v92
	v_mul_f32_e32 v93, v230, v93
	v_exp_f32_e32 v94, v94
	v_exp_f32_e32 v95, v95
	v_exp_f32_e32 v96, v96
	v_exp_f32_e32 v97, v97
	v_exp_f32_e32 v90, v90
	v_exp_f32_e32 v91, v91
	v_exp_f32_e32 v92, v92
	v_exp_f32_e32 v93, v93
	v_fma_f32 v94, v94, v231, v231
	v_fma_f32 v95, v95, v231, v231
	v_fma_f32 v96, v96, v231, v231
	v_fma_f32 v97, v97, v231, v231
	v_fma_f32 v90, v90, v231, v231
	v_fma_f32 v91, v91, v231, v231
	v_fma_f32 v92, v92, v231, v231
	v_fma_f32 v93, v93, v231, v231
	v_rcp_f32_e32 v94, v94
	v_rcp_f32_e32 v95, v95
	v_rcp_f32_e32 v96, v96
	v_rcp_f32_e32 v97, v97
	v_rcp_f32_e32 v90, v90
	v_rcp_f32_e32 v91, v91
	v_rcp_f32_e32 v92, v92
	v_rcp_f32_e32 v93, v93
	v_mul_f32_e32 v86, v86, v94
	v_mul_f32_e32 v87, v87, v95
	v_mul_f32_e32 v88, v88, v96
	v_mul_f32_e32 v89, v89, v97
	v_mul_f32_e32 v82, v82, v90
; __device__ __forceinline__ unsigned cvt_pk_bf16(float lo, float hi) { unsigned r; asm volatile("v_cvt_pk_bf16_f32 %0, %1, %2" : "=v"(r) : "v"(lo), "v"(hi)); return r; }
; #define LAS __attribute__((address_space(3)))
; __device__ __forceinline__ float sigmoid_f(float x) { return __builtin_amdgcn_rcpf(1.0f + __builtin_amdgcn_exp2f(-1.4426950408889634f * x)); }
; __device__ __forceinline__ float rstd4(const f32x4 q) { return __builtin_amdgcn_rsqf(((q[0] + q[1]) + (q[2] + q[3])) * (1.0f / DM) + EPS); }
;     __device__ __forceinline__ void operator()(const f32x4 (&acc)[2][2][4][2], const pg8::Unit& u, int wr, int wc, int fr, int fq, LAS unsigned char* lds, int wid, int lane, const pg8::Unit& nxt, bool has_next, int ui) const {
;     ...
;             for (int m = 0; m < 4; ++m) {
;                 const int row = row0 + ai * 128 + m * 16; const float r_ = R[wr * 64 + fr + ai * 128 + m * 16];
;                 const f32x4 g0 = acc[ai][0][m][0] * r_, g1 = acc[ai][0][m][1] * r_, u0 = acc[ai][1][m][0] * r_, u1 = acc[ai][1][m][1] * r_;
;                 v4u w;
;                 w.x = cvt_pk_bf16(g0[0] * sigmoid_f(g0[0]) * u0[0], g0[1] * sigmoid_f(g0[1]) * u0[1]); w.y = cvt_pk_bf16(g0[2] * sigmoid_f(g0[2]) * u0[2], g0[3] * sigmoid_f(g0[3]) * u0[3]);
;                 w.z = cvt_pk_bf16(g1[0] * sigmoid_f(g1[0]) * u1[0], g1[1] * sigmoid_f(g1[1]) * u1[1]); w.w = cvt_pk_bf16(g1[2] * sigmoid_f(g1[2]) * u1[2], g1[3] * sigmoid_f(g1[3]) * u1[3]);
;                 *(v4u*)(ACT + (size_t)row * FF + col) = w;
;             }
;             if (ai == 0) {
;                 __builtin_amdgcn_sched_barrier(0);
;                 float rn = rstd4(qn); asm volatile("" : "+v"(rn));
;                 if (pre) ((LAS float*)(lds + RS_OFF))[((ui + 1) & 1) * 256 + tid] = rn;
;                 __builtin_amdgcn_sched_barrier(0);
	v_mul_f32_e32 v83, v83, v91
	v_mul_f32_e32 v84, v84, v92
	v_mul_f32_e32 v85, v85, v93
	v_cvt_pk_bf16_f32 v86, v86, v87
	v_cvt_pk_bf16_f32 v87, v88, v89
	v_cvt_pk_bf16_f32 v88, v82, v83
	v_cvt_pk_bf16_f32 v89, v84, v85
	v_or_b32_e32 v226, 32, v236
	v_mad_i64_i32 v[228:229], s[12:13], v226, s55, v[224:225]
	global_store_dwordx4 v[228:229], v[86:89], off
	v_mul_f32_e32 v230, 0xbfb8aa3b, v238
	v_mul_f32_e32 v231, v238, v238
	v_rcp_f32_e32 v231, v231
	v_mul_f32_e32 v70, v78, v70
	v_mul_f32_e32 v71, v79, v71
	v_mul_f32_e32 v72, v80, v72
	v_mul_f32_e32 v73, v81, v73
	v_mul_f32_e32 v66, v74, v66
	v_mul_f32_e32 v67, v75, v67
	v_mul_f32_e32 v68, v76, v68
	v_mul_f32_e32 v69, v77, v69
	v_mul_f32_e32 v78, v230, v78
	v_mul_f32_e32 v79, v230, v79
	v_mul_f32_e32 v80, v230, v80
	v_mul_f32_e32 v81, v230, v81
	v_mul_f32_e32 v74, v230, v74
	v_mul_f32_e32 v75, v230, v75
	v_mul_f32_e32 v76, v230, v76
	v_mul_f32_e32 v77, v230, v77
	v_exp_f32_e32 v78, v78
	v_exp_f32_e32 v79, v79
	v_exp_f32_e32 v80, v80
	v_exp_f32_e32 v81, v81
	v_exp_f32_e32 v74, v74
	v_exp_f32_e32 v75, v75
	v_exp_f32_e32 v76, v76
	v_exp_f32_e32 v77, v77
	v_fma_f32 v78, v78, v231, v231
	v_fma_f32 v79, v79, v231, v231
	v_fma_f32 v80, v80, v231, v231
	v_fma_f32 v81, v81, v231, v231
	v_fma_f32 v74, v74, v231, v231
	v_fma_f32 v75, v75, v231, v231
	v_fma_f32 v76, v76, v231, v231
	v_fma_f32 v77, v77, v231, v231
	v_rcp_f32_e32 v78, v78
	v_rcp_f32_e32 v79, v79
	v_rcp_f32_e32 v80, v80
	v_rcp_f32_e32 v81, v81
	v_rcp_f32_e32 v74, v74
	v_rcp_f32_e32 v75, v75
	v_rcp_f32_e32 v76, v76
	v_rcp_f32_e32 v77, v77
	v_mul_f32_e32 v70, v70, v78
	v_mul_f32_e32 v71, v71, v79
	v_mul_f32_e32 v72, v72, v80
	v_mul_f32_e32 v73, v73, v81
	v_mul_f32_e32 v66, v66, v74
	v_mul_f32_e32 v67, v67, v75
	v_mul_f32_e32 v68, v68, v76
	v_mul_f32_e32 v69, v69, v77
	v_cvt_pk_bf16_f32 v70, v70, v71
	v_cvt_pk_bf16_f32 v71, v72, v73
	v_cvt_pk_bf16_f32 v72, v66, v67
	v_cvt_pk_bf16_f32 v73, v68, v69
	v_or_b32_e32 v226, 48, v236
	v_mad_i64_i32 v[228:229], s[12:13], v226, s55, v[224:225]
	global_store_dwordx4 v[228:229], v[70:73], off
	s_waitcnt vmcnt(4)
	s_nop 0
	v_add_f32_e32 v233, v98, v99
	v_add_f32_e32 v226, v100, v101
	v_add_f32_e32 v233, v233, v226
	v_fmamk_f32 v233, v233, 0x3a800000, v245
	v_rsq_f32_e32 v233, v233
	s_and_saveexec_b64 s[22:23], s[20:21]
	s_xor_b32 s11, s11, 0x100
	v_lshl_add_u32 v226, s11, 2, v152
	ds_write_b32 v226, v233
	s_or_b64 exec, exec, s[22:23]
	s_mov_b64 s[20:21], -1
	s_cmp_eq_u32 s82, 21
	v_add_u32_e32 v234, 0x10000, v150
	v_add_u32_e32 v235, 0x14000, v150
	ds_read_b128 v[98:101], v234
	ds_read_b128 v[156:159], v234 offset:1024
	ds_read_b128 v[160:163], v234 offset:2048
	ds_read_b128 v[164:167], v234 offset:3072
	ds_read_b128 v[168:171], v235
	ds_read_b128 v[172:175], v235 offset:1024
	ds_read_b128 v[176:179], v235 offset:2048
	ds_read_b128 v[180:183], v235 offset:3072
	ds_read_b128 v[184:187], v154
	ds_read_b128 v[188:191], v154 offset:1024
	ds_read_b128 v[192:195], v154 offset:2048
	ds_read_b128 v[196:199], v154 offset:3072
	ds_read_b128 v[200:203], v154 offset:4096
	ds_read_b128 v[204:207], v154 offset:5120
	ds_read_b128 v[208:211], v154 offset:6144
	ds_read_b128 v[214:217], v154 offset:7168
	v_mul_f32_e32 v230, 0xbfb8aa3b, v239
	v_mul_f32_e32 v231, v239, v239
	v_rcp_f32_e32 v231, v231
	v_mul_f32_e32 v54, v62, v54
	v_mul_f32_e32 v55, v63, v55
	v_mul_f32_e32 v56, v64, v56
	v_mul_f32_e32 v57, v65, v57
	v_mul_f32_e32 v50, v58, v50
	v_mul_f32_e32 v51, v59, v51
	v_mul_f32_e32 v52, v60, v52
	v_mul_f32_e32 v53, v61, v53
	v_mul_f32_e32 v62, v230, v62
	v_mul_f32_e32 v63, v230, v63
	v_mul_f32_e32 v64, v230, v64
	v_mul_f32_e32 v65, v230, v65
	v_mul_f32_e32 v58, v230, v58
	v_mul_f32_e32 v59, v230, v59
	v_mul_f32_e32 v60, v230, v60
	v_mul_f32_e32 v61, v230, v61
	v_exp_f32_e32 v62, v62
	v_exp_f32_e32 v63, v63
	v_exp_f32_e32 v64, v64
	v_exp_f32_e32 v65, v65
	v_exp_f32_e32 v58, v58
	v_exp_f32_e32 v59, v59
	v_exp_f32_e32 v60, v60
	v_exp_f32_e32 v61, v61
	v_fma_f32 v62, v62, v231, v231
	v_fma_f32 v63, v63, v231, v231
	v_fma_f32 v64, v64, v231, v231
	v_fma_f32 v65, v65, v231, v231
	v_fma_f32 v58, v58, v231, v231
	v_fma_f32 v59, v59, v231, v231
	v_fma_f32 v60, v60, v231, v231
	v_fma_f32 v61, v61, v231, v231
	v_rcp_f32_e32 v62, v62
	v_rcp_f32_e32 v63, v63
	v_rcp_f32_e32 v64, v64
	v_rcp_f32_e32 v65, v65
	v_rcp_f32_e32 v58, v58
	v_rcp_f32_e32 v59, v59
	v_rcp_f32_e32 v60, v60
	v_rcp_f32_e32 v61, v61
	v_mul_f32_e32 v54, v54, v62
	v_mul_f32_e32 v55, v55, v63
	v_mul_f32_e32 v56, v56, v64
	v_mul_f32_e32 v57, v57, v65
	v_mul_f32_e32 v50, v50, v58
	v_mul_f32_e32 v51, v51, v59
	v_mul_f32_e32 v52, v52, v60
	v_mul_f32_e32 v53, v53, v61
	v_cvt_pk_bf16_f32 v54, v54, v55
	v_cvt_pk_bf16_f32 v55, v56, v57
	v_cvt_pk_bf16_f32 v56, v50, v51
	v_cvt_pk_bf16_f32 v57, v52, v53
	v_or_b32_e32 v226, 0x80, v236
	v_mad_i64_i32 v[228:229], s[12:13], v226, s55, v[224:225]
	global_store_dwordx4 v[228:229], v[54:57], off
	v_mul_f32_e32 v230, 0xbfb8aa3b, v240
	v_mul_f32_e32 v231, v240, v240
	v_rcp_f32_e32 v231, v231
	v_mul_f32_e32 v38, v46, v38
	v_mul_f32_e32 v39, v47, v39
; __device__ __forceinline__ unsigned cvt_pk_bf16(float lo, float hi) { unsigned r; asm volatile("v_cvt_pk_bf16_f32 %0, %1, %2" : "=v"(r) : "v"(lo), "v"(hi)); return r; }
; #define PG8_BAR __builtin_amdgcn_s_barrier()
; __device__ __forceinline__ float sigmoid_f(float x) { return __builtin_amdgcn_rcpf(1.0f + __builtin_amdgcn_exp2f(-1.4426950408889634f * x)); }
; template <class Epi, class Sched>
; __device__ __forceinline__ void gemm_phase(PG8_LAS unsigned char* lds, const Gemm g, const Sched& S, const Epi& E) {
;     ...
;         cur = nxt; cA = nA; cB = nB; ++ui;
;         if (wr == 1) PG8_BAR;
;     __device__ __forceinline__ void operator()(const f32x4 (&acc)[2][2][4][2], const pg8::Unit& u, int wr, int wc, int fr, int fq, LAS unsigned char* lds, int wid, int lane, const pg8::Unit& nxt, bool has_next, int ui) const {
;     ...
;             for (int m = 0; m < 4; ++m) {
;                 const int row = row0 + ai * 128 + m * 16; const float r_ = R[wr * 64 + fr + ai * 128 + m * 16];
;                 const f32x4 g0 = acc[ai][0][m][0] * r_, g1 = acc[ai][0][m][1] * r_, u0 = acc[ai][1][m][0] * r_, u1 = acc[ai][1][m][1] * r_;
;                 v4u w;
;                 w.x = cvt_pk_bf16(g0[0] * sigmoid_f(g0[0]) * u0[0], g0[1] * sigmoid_f(g0[1]) * u0[1]); w.y = cvt_pk_bf16(g0[2] * sigmoid_f(g0[2]) * u0[2], g0[3] * sigmoid_f(g0[3]) * u0[3]);
;                 w.z = cvt_pk_bf16(g1[0] * sigmoid_f(g1[0]) * u1[0], g1[1] * sigmoid_f(g1[1]) * u1[1]); w.w = cvt_pk_bf16(g1[2] * sigmoid_f(g1[2]) * u1[2], g1[3] * sigmoid_f(g1[3]) * u1[3]);
;                 *(v4u*)(ACT + (size_t)row * FF + col) = w;
	v_mul_f32_e32 v40, v48, v40
	v_mul_f32_e32 v41, v49, v41
	v_mul_f32_e32 v34, v42, v34
	v_mul_f32_e32 v35, v43, v35
	v_mul_f32_e32 v36, v44, v36
	v_mul_f32_e32 v37, v45, v37
	v_mul_f32_e32 v46, v230, v46
	v_mul_f32_e32 v47, v230, v47
	v_mul_f32_e32 v48, v230, v48
	v_mul_f32_e32 v49, v230, v49
	v_mul_f32_e32 v42, v230, v42
	v_mul_f32_e32 v43, v230, v43
	v_mul_f32_e32 v44, v230, v44
	v_mul_f32_e32 v45, v230, v45
	v_exp_f32_e32 v46, v46
	v_exp_f32_e32 v47, v47
	v_exp_f32_e32 v48, v48
	v_exp_f32_e32 v49, v49
	v_exp_f32_e32 v42, v42
	v_exp_f32_e32 v43, v43
	v_exp_f32_e32 v44, v44
	v_exp_f32_e32 v45, v45
	v_fma_f32 v46, v46, v231, v231
	v_fma_f32 v47, v47, v231, v231
	v_fma_f32 v48, v48, v231, v231
	v_fma_f32 v49, v49, v231, v231
	v_fma_f32 v42, v42, v231, v231
	v_fma_f32 v43, v43, v231, v231
	v_fma_f32 v44, v44, v231, v231
	v_fma_f32 v45, v45, v231, v231
	v_rcp_f32_e32 v46, v46
	v_rcp_f32_e32 v47, v47
	v_rcp_f32_e32 v48, v48
	v_rcp_f32_e32 v49, v49
	v_rcp_f32_e32 v42, v42
	v_rcp_f32_e32 v43, v43
	v_rcp_f32_e32 v44, v44
	v_rcp_f32_e32 v45, v45
	v_mul_f32_e32 v38, v38, v46
	v_mul_f32_e32 v39, v39, v47
	v_mul_f32_e32 v40, v40, v48
	v_mul_f32_e32 v41, v41, v49
	v_mul_f32_e32 v34, v34, v42
	v_mul_f32_e32 v35, v35, v43
	v_mul_f32_e32 v36, v36, v44
	v_mul_f32_e32 v37, v37, v45
	v_cvt_pk_bf16_f32 v38, v38, v39
	v_cvt_pk_bf16_f32 v39, v40, v41
	v_cvt_pk_bf16_f32 v40, v34, v35
	v_cvt_pk_bf16_f32 v41, v36, v37
	v_or_b32_e32 v226, 0x90, v236
	v_mad_i64_i32 v[228:229], s[12:13], v226, s55, v[224:225]
	global_store_dwordx4 v[228:229], v[38:41], off
	v_mul_f32_e32 v230, 0xbfb8aa3b, v241
	v_mul_f32_e32 v231, v241, v241
	v_rcp_f32_e32 v231, v231
	v_mul_f32_e32 v22, v30, v22
	v_mul_f32_e32 v23, v31, v23
	v_mul_f32_e32 v24, v32, v24
	v_mul_f32_e32 v25, v33, v25
	v_mul_f32_e32 v18, v26, v18
	v_mul_f32_e32 v19, v27, v19
	v_mul_f32_e32 v20, v28, v20
	v_mul_f32_e32 v21, v29, v21
	v_mul_f32_e32 v30, v230, v30
	v_mul_f32_e32 v31, v230, v31
	v_mul_f32_e32 v32, v230, v32
	v_mul_f32_e32 v33, v230, v33
	v_mul_f32_e32 v26, v230, v26
	v_mul_f32_e32 v27, v230, v27
	v_mul_f32_e32 v28, v230, v28
	v_mul_f32_e32 v29, v230, v29
	v_exp_f32_e32 v30, v30
	v_exp_f32_e32 v31, v31
	v_exp_f32_e32 v32, v32
	v_exp_f32_e32 v33, v33
	v_exp_f32_e32 v26, v26
	v_exp_f32_e32 v27, v27
	v_exp_f32_e32 v28, v28
	v_exp_f32_e32 v29, v29
	v_fma_f32 v30, v30, v231, v231
	v_fma_f32 v31, v31, v231, v231
	v_fma_f32 v32, v32, v231, v231
	v_fma_f32 v33, v33, v231, v231
	v_fma_f32 v26, v26, v231, v231
	v_fma_f32 v27, v27, v231, v231
	v_fma_f32 v28, v28, v231, v231
	v_fma_f32 v29, v29, v231, v231
	v_rcp_f32_e32 v30, v30
	v_rcp_f32_e32 v31, v31
	v_rcp_f32_e32 v32, v32
	v_rcp_f32_e32 v33, v33
	v_rcp_f32_e32 v26, v26
	v_rcp_f32_e32 v27, v27
	v_rcp_f32_e32 v28, v28
	v_rcp_f32_e32 v29, v29
	v_mul_f32_e32 v22, v22, v30
	v_mul_f32_e32 v23, v23, v31
	v_mul_f32_e32 v24, v24, v32
	v_mul_f32_e32 v25, v25, v33
	v_mul_f32_e32 v18, v18, v26
	v_mul_f32_e32 v19, v19, v27
	v_mul_f32_e32 v20, v20, v28
	v_mul_f32_e32 v21, v21, v29
	v_cvt_pk_bf16_f32 v22, v22, v23
	v_cvt_pk_bf16_f32 v23, v24, v25
	v_cvt_pk_bf16_f32 v24, v18, v19
	v_cvt_pk_bf16_f32 v25, v20, v21
	v_or_b32_e32 v226, 0xa0, v236
	v_mad_i64_i32 v[228:229], s[12:13], v226, s55, v[224:225]
	global_store_dwordx4 v[228:229], v[22:25], off
	v_mul_f32_e32 v230, 0xbfb8aa3b, v242
	v_mul_f32_e32 v231, v242, v242
	v_rcp_f32_e32 v231, v231
	v_mul_f32_e32 v6, v14, v6
	v_mul_f32_e32 v7, v15, v7
	v_mul_f32_e32 v8, v16, v8
	v_mul_f32_e32 v9, v17, v9
	v_mul_f32_e32 v2, v10, v2
	v_mul_f32_e32 v3, v11, v3
	v_mul_f32_e32 v4, v12, v4
	v_mul_f32_e32 v5, v13, v5
	v_mul_f32_e32 v14, v230, v14
	v_mul_f32_e32 v15, v230, v15
	v_mul_f32_e32 v16, v230, v16
	v_mul_f32_e32 v17, v230, v17
	v_mul_f32_e32 v10, v230, v10
	v_mul_f32_e32 v11, v230, v11
	v_mul_f32_e32 v12, v230, v12
	v_mul_f32_e32 v13, v230, v13
	v_exp_f32_e32 v14, v14
	v_exp_f32_e32 v15, v15
	v_exp_f32_e32 v16, v16
	v_exp_f32_e32 v17, v17
	v_exp_f32_e32 v10, v10
	v_exp_f32_e32 v11, v11
	v_exp_f32_e32 v12, v12
	v_exp_f32_e32 v13, v13
	v_fma_f32 v14, v14, v231, v231
	v_fma_f32 v15, v15, v231, v231
	v_fma_f32 v16, v16, v231, v231
	v_fma_f32 v17, v17, v231, v231
	v_fma_f32 v10, v10, v231, v231
	v_fma_f32 v11, v11, v231, v231
	v_fma_f32 v12, v12, v231, v231
	v_fma_f32 v13, v13, v231, v231
	v_rcp_f32_e32 v14, v14
	v_rcp_f32_e32 v15, v15
	v_rcp_f32_e32 v16, v16
	v_rcp_f32_e32 v17, v17
	v_rcp_f32_e32 v10, v10
	v_rcp_f32_e32 v11, v11
	v_rcp_f32_e32 v12, v12
	v_rcp_f32_e32 v13, v13
	v_mul_f32_e32 v6, v6, v14
	v_mul_f32_e32 v7, v7, v15
	v_mul_f32_e32 v8, v8, v16
	v_mul_f32_e32 v9, v9, v17
	v_mul_f32_e32 v2, v2, v10
	v_mul_f32_e32 v3, v3, v11
	v_mul_f32_e32 v4, v4, v12
	v_mul_f32_e32 v5, v5, v13
	v_cvt_pk_bf16_f32 v6, v6, v7
	v_cvt_pk_bf16_f32 v7, v8, v9
	v_cvt_pk_bf16_f32 v8, v2, v3
	v_cvt_pk_bf16_f32 v9, v4, v5
	v_or_b32_e32 v226, 0xb0, v236
	v_mad_i64_i32 v[228:229], s[12:13], v226, s55, v[224:225]
	global_store_dwordx4 v[228:229], v[6:9], off
	s_cbranch_scc1 .LBB0_574
	s_andn2_b64 vcc, exec, s[6:7]
	s_cbranch_vccnz .LBB0_573
	s_barrier
	s_branch .LBB0_573
